# GEMM K-loop: all six stage DMAs interleaved with the MFMAs
# speedup vs baseline: 1.0123x; 1.0045x over previous
.LBB0_246:
	s_add_i32 s10, s7, 0xffffa000
	s_cmp_lg_u32 s7, 0
	s_cselect_b32 s12, s10, 0xc000
	v_add_u32_e32 v131, s7, v150
	s_waitcnt vmcnt(6)
	s_barrier
	v_add_u32_e32 v133, s7, v149
	ds_read_b128 v[154:157], v131 offset:0
	ds_read_b128 v[158:161], v131 offset:0x400
	ds_read_b128 v[162:165], v131 offset:0x800
	ds_read_b128 v[166:169], v131 offset:0xc00
	v_add_u32_e32 v131, s12, v147
	ds_read_b128 v[170:173], v133 offset:0
	ds_read_b128 v[174:177], v133 offset:0x400
	ds_read_b128 v[178:181], v133 offset:0x800
	ds_read_b128 v[200:203], v133 offset:0xc00
	s_add_u32 s10, s8, s50
	s_addc_u32 s11, s9, s51
	v_readfirstlane_b32 s13, v131
	s_add_u32 s64, s5, s100
	s_addc_u32 s65, s6, 0
	s_sub_i32 s68, s13, s12
	s_lshr_b32 s68, s68, 1
	s_add_i32 s68, s68, s12
	s_addk_i32 s68, 0x4000
	s_waitcnt lgkmcnt(0)
	s_nop 0
	v_mfma_f32_16x16x32_bf16 v[126:129], v[154:157], v[170:173], v[126:129]
	ds_read_b128 v[204:207], v133 offset:0x1000
	v_mfma_f32_16x16x32_bf16 v[122:125], v[154:157], v[174:177], v[122:125]
	ds_read_b128 v[208:211], v133 offset:0x1400
	v_mfma_f32_16x16x32_bf16 v[118:121], v[154:157], v[178:181], v[118:121]
	ds_read_b128 v[212:215], v133 offset:0x1800
	v_mfma_f32_16x16x32_bf16 v[114:117], v[154:157], v[200:203], v[114:117]
	ds_read_b128 v[216:219], v133 offset:0x1c00
	v_mfma_f32_16x16x32_bf16 v[110:113], v[158:161], v[170:173], v[110:113]
	s_mov_b32 m0, s13
	s_nop 0
	global_load_lds_dwordx4 v0, s[10:11]
	v_mfma_f32_16x16x32_bf16 v[102:105], v[158:161], v[174:177], v[102:105]
	v_mfma_f32_16x16x32_bf16 v[94:97], v[158:161], v[178:181], v[94:97]
	v_mfma_f32_16x16x32_bf16 v[86:89], v[158:161], v[200:203], v[86:89]
	s_add_u32 m0, s13, 0x400
	s_nop 0
	global_load_lds_dwordx4 v130, s[10:11]
	v_mfma_f32_16x16x32_bf16 v[78:81], v[162:165], v[170:173], v[78:81]
	v_mfma_f32_16x16x32_bf16 v[70:73], v[162:165], v[174:177], v[70:73]
	v_mfma_f32_16x16x32_bf16 v[62:65], v[162:165], v[178:181], v[62:65]
	s_add_u32 m0, s13, 0x800
	s_nop 0
	global_load_lds_dwordx4 v132, s[10:11]
	v_mfma_f32_16x16x32_bf16 v[54:57], v[162:165], v[200:203], v[54:57]
	v_mfma_f32_16x16x32_bf16 v[46:49], v[166:169], v[170:173], v[46:49]
	v_mfma_f32_16x16x32_bf16 v[38:41], v[166:169], v[174:177], v[38:41]
	s_add_u32 m0, s13, 0xc00
	s_nop 0
	global_load_lds_dwordx4 v136, s[10:11]
	v_mfma_f32_16x16x32_bf16 v[30:33], v[166:169], v[178:181], v[30:33]
	v_mfma_f32_16x16x32_bf16 v[22:25], v[166:169], v[200:203], v[22:25]
	s_mov_b32 m0, s68
	s_nop 0
	global_load_lds_dwordx4 v138, s[64:65]
	s_waitcnt lgkmcnt(0)
	s_nop 0
	v_mfma_f32_16x16x32_bf16 v[106:109], v[154:157], v[204:207], v[106:109]
	v_mfma_f32_16x16x32_bf16 v[98:101], v[154:157], v[208:211], v[98:101]
	v_mfma_f32_16x16x32_bf16 v[90:93], v[154:157], v[212:215], v[90:93]
	v_mfma_f32_16x16x32_bf16 v[82:85], v[154:157], v[216:219], v[82:85]
	v_mfma_f32_16x16x32_bf16 v[74:77], v[158:161], v[204:207], v[74:77]
	v_mfma_f32_16x16x32_bf16 v[66:69], v[158:161], v[208:211], v[66:69]
	s_add_u32 m0, s68, 0x400
	s_nop 0
	global_load_lds_dwordx4 v140, s[64:65]
	v_mfma_f32_16x16x32_bf16 v[58:61], v[158:161], v[212:215], v[58:61]
	v_mfma_f32_16x16x32_bf16 v[50:53], v[158:161], v[216:219], v[50:53]
	v_mfma_f32_16x16x32_bf16 v[42:45], v[162:165], v[204:207], v[42:45]
	v_mfma_f32_16x16x32_bf16 v[34:37], v[162:165], v[208:211], v[34:37]
	v_mfma_f32_16x16x32_bf16 v[26:29], v[162:165], v[212:215], v[26:29]
	v_mfma_f32_16x16x32_bf16 v[18:21], v[162:165], v[216:219], v[18:21]
	v_mfma_f32_16x16x32_bf16 v[14:17], v[166:169], v[204:207], v[14:17]
	v_mfma_f32_16x16x32_bf16 v[10:13], v[166:169], v[208:211], v[10:13]
	v_mfma_f32_16x16x32_bf16 v[6:9], v[166:169], v[212:215], v[6:9]
	v_mfma_f32_16x16x32_bf16 v[2:5], v[166:169], v[216:219], v[2:5]
	s_add_i32 s10, s7, 0x6000
	s_cmpk_lg_u32 s7, 0xc000
	s_cselect_b32 s7, s10, 0
	s_addk_i32 s100, 0x400
	s_add_u32 s50, s50, s60
	s_addc_u32 s51, s51, 0
	s_cmpk_lg_i32 s100, 0x7800
	s_cbranch_scc1 .LBB0_246
	s_waitcnt vmcnt(6)
	s_barrier
	v_add_u32_e32 v0, s7, v150
	v_add_u32_e32 v140, s7, v149
	ds_read_b128 v[130:133], v0 offset:0
	ds_read_b128 v[136:139], v0 offset:0x400
	ds_read_b128 v[154:157], v0 offset:0x800
	ds_read_b128 v[158:161], v0 offset:0xc00
	ds_read_b128 v[162:165], v140 offset:0
	ds_read_b128 v[166:169], v140 offset:0x400
	ds_read_b128 v[170:173], v140 offset:0x800
	ds_read_b128 v[174:177], v140 offset:0xc00
	ds_read_b128 v[178:181], v140 offset:0x1000
	ds_read_b128 v[200:203], v140 offset:0x1400
	ds_read_b128 v[204:207], v140 offset:0x1800
	ds_read_b128 v[208:211], v140 offset:0x1c00
	s_lshl_b32 s49, s4, 8
	s_waitcnt lgkmcnt(4)
	s_nop 0
	v_mfma_f32_16x16x32_bf16 v[126:129], v[130:133], v[162:165], v[126:129]
	v_mfma_f32_16x16x32_bf16 v[118:121], v[130:133], v[170:173], v[118:121]
	v_mfma_f32_16x16x32_bf16 v[114:117], v[130:133], v[174:177], v[114:117]
	v_mfma_f32_16x16x32_bf16 v[110:113], v[136:139], v[162:165], v[110:113]
	v_mfma_f32_16x16x32_bf16 v[102:105], v[136:139], v[166:169], v[102:105]
	v_mfma_f32_16x16x32_bf16 v[94:97], v[136:139], v[170:173], v[94:97]
	v_mfma_f32_16x16x32_bf16 v[86:89], v[136:139], v[174:177], v[86:89]
	v_mfma_f32_16x16x32_bf16 v[70:73], v[154:157], v[166:169], v[70:73]
	v_mfma_f32_16x16x32_bf16 v[62:65], v[154:157], v[170:173], v[62:65]
	v_mfma_f32_16x16x32_bf16 v[54:57], v[154:157], v[174:177], v[54:57]
	v_mfma_f32_16x16x32_bf16 v[46:49], v[158:161], v[162:165], v[46:49]
	v_mfma_f32_16x16x32_bf16 v[38:41], v[158:161], v[166:169], v[38:41]
	v_mfma_f32_16x16x32_bf16 v[30:33], v[158:161], v[170:173], v[30:33]
	v_mfma_f32_16x16x32_bf16 v[22:25], v[158:161], v[174:177], v[22:25]
	v_mfma_f32_16x16x32_bf16 v[212:215], v[130:133], v[166:169], v[122:125]
	v_mfma_f32_16x16x32_bf16 v[216:219], v[154:157], v[162:165], v[78:81]
	s_waitcnt lgkmcnt(0)
	s_nop 0
	v_mfma_f32_16x16x32_bf16 v[174:177], v[136:139], v[178:181], v[74:77]
	v_mfma_f32_16x16x32_bf16 v[220:223], v[136:139], v[200:203], v[66:69]
	v_mfma_f32_16x16x32_bf16 v[224:227], v[136:139], v[204:207], v[58:61]
	v_mfma_f32_16x16x32_bf16 v[50:53], v[136:139], v[208:211], v[50:53]
	v_mfma_f32_16x16x32_bf16 v[136:139], v[154:157], v[178:181], v[42:45]
	v_mfma_f32_16x16x32_bf16 v[34:37], v[154:157], v[200:203], v[34:37]
	v_mfma_f32_16x16x32_bf16 v[6:9], v[158:161], v[204:207], v[6:9]
	v_mfma_f32_16x16x32_bf16 v[162:165], v[130:133], v[178:181], v[106:109]
	v_mfma_f32_16x16x32_bf16 v[166:169], v[130:133], v[200:203], v[98:101]
	v_mfma_f32_16x16x32_bf16 v[170:173], v[130:133], v[204:207], v[90:93]
	v_mfma_f32_16x16x32_bf16 v[130:133], v[130:133], v[208:211], v[82:85]
	v_mfma_f32_16x16x32_bf16 v[228:231], v[154:157], v[204:207], v[26:29]
	v_mfma_f32_16x16x32_bf16 v[154:157], v[154:157], v[208:211], v[18:21]
	v_mfma_f32_16x16x32_bf16 v[178:181], v[158:161], v[178:181], v[14:17]
	v_mfma_f32_16x16x32_bf16 v[200:203], v[158:161], v[200:203], v[10:13]
	v_mfma_f32_16x16x32_bf16 v[158:161], v[158:161], v[208:211], v[2:5]
	s_waitcnt vmcnt(0)
	s_barrier
	ds_read_b128 v[2:5], v151 offset:0
	ds_read_b128 v[14:17], v151 offset:0x400
	ds_read_b128 v[204:207], v151 offset:0x800
	ds_read_b128 v[208:211], v151 offset:0xc00
	ds_read_b128 v[10:13], v152 offset:0
	ds_read_b128 v[18:21], v152 offset:0x400
	ds_read_b128 v[26:29], v152 offset:0x800
	ds_read_b128 v[42:45], v152 offset:0xc00
	ds_read_b128 v[232:235], v152 offset:0x1000
	ds_read_b128 v[236:239], v152 offset:0x1400
	ds_read_b128 v[240:243], v152 offset:0x1800
	ds_read_b128 v[244:247], v152 offset:0x1c00
	s_nop 0
	s_waitcnt lgkmcnt(4)
	s_nop 0
	v_mfma_f32_16x16x32_bf16 v[122:125], v[2:5], v[10:13], v[126:129]
	v_mfma_f32_16x16x32_bf16 v[106:109], v[2:5], v[18:21], v[212:215]
	v_mfma_f32_16x16x32_bf16 v[90:93], v[2:5], v[26:29], v[118:121]
	v_mfma_f32_16x16x32_bf16 v[74:77], v[2:5], v[42:45], v[114:117]
	v_mfma_f32_16x16x32_bf16 v[126:129], v[14:17], v[10:13], v[110:113]
	v_mfma_f32_16x16x32_bf16 v[110:113], v[14:17], v[18:21], v[102:105]
	v_mfma_f32_16x16x32_bf16 v[94:97], v[14:17], v[26:29], v[94:97]
	v_mfma_f32_16x16x32_bf16 v[78:81], v[14:17], v[42:45], v[86:89]
	v_mfma_f32_16x16x32_bf16 v[114:117], v[204:207], v[10:13], v[216:219]
	v_mfma_f32_16x16x32_bf16 v[98:101], v[204:207], v[18:21], v[70:73]
	v_mfma_f32_16x16x32_bf16 v[82:85], v[204:207], v[26:29], v[62:65]
	v_mfma_f32_16x16x32_bf16 v[66:69], v[204:207], v[42:45], v[54:57]
	v_mfma_f32_16x16x32_bf16 v[118:121], v[208:211], v[10:13], v[46:49]
	v_mfma_f32_16x16x32_bf16 v[102:105], v[208:211], v[18:21], v[38:41]
	v_mfma_f32_16x16x32_bf16 v[86:89], v[208:211], v[26:29], v[30:33]
	v_mfma_f32_16x16x32_bf16 v[70:73], v[208:211], v[42:45], v[22:25]
	s_waitcnt lgkmcnt(0)
	s_nop 0
	v_mfma_f32_16x16x32_bf16 v[58:61], v[2:5], v[232:235], v[162:165]
	v_mfma_f32_16x16x32_bf16 v[42:45], v[2:5], v[236:239], v[166:169]
	v_mfma_f32_16x16x32_bf16 v[26:29], v[2:5], v[240:243], v[170:173]
	v_mfma_f32_16x16x32_bf16 v[10:13], v[2:5], v[244:247], v[130:133]
	v_mfma_f32_16x16x32_bf16 v[62:65], v[14:17], v[232:235], v[174:177]
	v_mfma_f32_16x16x32_bf16 v[46:49], v[14:17], v[236:239], v[220:223]
	v_mfma_f32_16x16x32_bf16 v[30:33], v[14:17], v[240:243], v[224:227]
	v_mfma_f32_16x16x32_bf16 v[14:17], v[14:17], v[244:247], v[50:53]
	v_mfma_f32_16x16x32_bf16 v[50:53], v[204:207], v[232:235], v[136:139]
	v_mfma_f32_16x16x32_bf16 v[34:37], v[204:207], v[236:239], v[34:37]
	v_mfma_f32_16x16x32_bf16 v[18:21], v[204:207], v[240:243], v[228:231]
	v_mfma_f32_16x16x32_bf16 v[2:5], v[204:207], v[244:247], v[154:157]
	v_mfma_f32_16x16x32_bf16 v[54:57], v[208:211], v[232:235], v[178:181]
	v_mfma_f32_16x16x32_bf16 v[38:41], v[208:211], v[236:239], v[200:203]
	v_mfma_f32_16x16x32_bf16 v[22:25], v[208:211], v[240:243], v[6:9]
	v_mfma_f32_16x16x32_bf16 v[6:9], v[208:211], v[244:247], v[158:161]
	v_mov_b32_e32 v136, v134
	s_mov_b64 s[50:51], -1
	s_and_b64 vcc, exec, s[22:23]
	s_barrier
	s_cbranch_vccz .LBB0_264
	s_and_b64 vcc, exec, s[0:1]
	s_cbranch_vccz .LBB0_250
	v_lshrrev_b32_e32 v0, 6, v136
	v_mul_lo_u32 v137, v0, s14
	v_and_b32_e32 v130, 15, v136
	v_and_or_b32 v0, v136, 48, v137
	s_movk_i32 s4, 0x90
	v_mad_u32_u24 v0, v130, s4, v0
	v_cvt_pk_bf16_f32 v130, v122, v123
	v_cvt_pk_bf16_f32 v131, v124, v125
	v_cvt_pk_bf16_f32 v132, v126, v127
	v_cvt_pk_bf16_f32 v133, v128, v129
	s_waitcnt vmcnt(0)
	ds_write_b128 v0, v[130:133]
	v_cvt_pk_bf16_f32 v130, v114, v115
	v_cvt_pk_bf16_f32 v131, v116, v117
	v_cvt_pk_bf16_f32 v132, v118, v119
	v_cvt_pk_bf16_f32 v133, v120, v121
	ds_write_b128 v0, v[130:133] offset:64
	v_cvt_pk_bf16_f32 v130, v106, v107
	v_cvt_pk_bf16_f32 v131, v108, v109
	v_cvt_pk_bf16_f32 v132, v110, v111
	v_cvt_pk_bf16_f32 v133, v112, v113
	ds_write_b128 v0, v[130:133] offset:2304
	v_cvt_pk_bf16_f32 v130, v98, v99
	v_cvt_pk_bf16_f32 v131, v100, v101
	v_cvt_pk_bf16_f32 v132, v102, v103
	v_cvt_pk_bf16_f32 v133, v104, v105
	ds_write_b128 v0, v[130:133] offset:2368
	v_cvt_pk_bf16_f32 v130, v90, v91
	v_cvt_pk_bf16_f32 v131, v92, v93
	v_cvt_pk_bf16_f32 v132, v94, v95
	v_cvt_pk_bf16_f32 v133, v96, v97
	ds_write_b128 v0, v[130:133] offset:4608
	v_cvt_pk_bf16_f32 v130, v82, v83
	v_cvt_pk_bf16_f32 v131, v84, v85
	v_cvt_pk_bf16_f32 v132, v86, v87
	v_cvt_pk_bf16_f32 v133, v88, v89
	ds_write_b128 v0, v[130:133] offset:4672
	v_cvt_pk_bf16_f32 v130, v74, v75
	v_cvt_pk_bf16_f32 v131, v76, v77
	v_cvt_pk_bf16_f32 v132, v78, v79
	v_cvt_pk_bf16_f32 v133, v80, v81
	ds_write_b128 v0, v[130:133] offset:6912
	v_cvt_pk_bf16_f32 v130, v66, v67
	v_cvt_pk_bf16_f32 v131, v68, v69
	v_cvt_pk_bf16_f32 v132, v70, v71
	v_cvt_pk_bf16_f32 v133, v72, v73
	ds_write_b128 v0, v[130:133] offset:6976
	v_cvt_pk_bf16_f32 v130, v58, v59
	v_cvt_pk_bf16_f32 v131, v60, v61
	v_cvt_pk_bf16_f32 v132, v62, v63
	v_cvt_pk_bf16_f32 v133, v64, v65
	ds_write_b128 v0, v[130:133] offset:9216
	v_cvt_pk_bf16_f32 v130, v50, v51
	v_cvt_pk_bf16_f32 v131, v52, v53
	v_cvt_pk_bf16_f32 v132, v54, v55
	v_cvt_pk_bf16_f32 v133, v56, v57
	ds_write_b128 v0, v[130:133] offset:9280
	v_cvt_pk_bf16_f32 v130, v42, v43
	v_cvt_pk_bf16_f32 v131, v44, v45
	v_cvt_pk_bf16_f32 v132, v46, v47
	v_cvt_pk_bf16_f32 v133, v48, v49
	ds_write_b128 v0, v[130:133] offset:11520
	v_cvt_pk_bf16_f32 v130, v34, v35
	v_cvt_pk_bf16_f32 v131, v36, v37
	v_cvt_pk_bf16_f32 v132, v38, v39
	v_cvt_pk_bf16_f32 v133, v40, v41
	ds_write_b128 v0, v[130:133] offset:11584
	v_cvt_pk_bf16_f32 v130, v26, v27
	v_cvt_pk_bf16_f32 v131, v28, v29
	v_cvt_pk_bf16_f32 v132, v30, v31
	v_cvt_pk_bf16_f32 v133, v32, v33
	ds_write_b128 v0, v[130:133] offset:13824
	v_cvt_pk_bf16_f32 v130, v18, v19
	v_cvt_pk_bf16_f32 v131, v20, v21
	v_cvt_pk_bf16_f32 v132, v22, v23
	v_cvt_pk_bf16_f32 v133, v24, v25
	ds_write_b128 v0, v[130:133] offset:13888
	v_cvt_pk_bf16_f32 v130, v10, v11
	v_cvt_pk_bf16_f32 v131, v12, v13
	v_cvt_pk_bf16_f32 v132, v14, v15
	v_cvt_pk_bf16_f32 v133, v16, v17
	ds_write_b128 v0, v[130:133] offset:16128
	v_cvt_pk_bf16_f32 v130, v2, v3
	v_cvt_pk_bf16_f32 v131, v4, v5
	v_cvt_pk_bf16_f32 v132, v6, v7
	v_cvt_pk_bf16_f32 v133, v8, v9
	ds_write_b128 v0, v[130:133] offset:16192
	v_and_b32_e32 v0, 0xffffff80, v136
	v_add_u32_e32 v130, s48, v0
	v_ashrrev_i32_e32 v131, 31, v130
	v_lshlrev_b64 v[130:131], 11, v[130:131]
	v_lshl_add_u64 v[130:131], s[38:39], 0, v[130:131]
	v_and_b32_e32 v0, 64, v136
	v_lshl_add_u64 v[130:131], s[46:47], 1, v[130:131]
	v_lshlrev_b32_e32 v0, 1, v0
	v_lshl_add_u64 v[138:139], v[130:131], 0, v[0:1]
	v_lshlrev_b32_e32 v0, 4, v136
	v_and_b32_e32 v0, 0x70, v0
	v_bfe_u32 v140, v136, 3, 3
	v_or_b32_e32 v130, v137, v0
	s_waitcnt lgkmcnt(0)
	v_mad_u32_u24 v137, v140, s4, v130
	ds_read_b128 v[130:133], v137
	v_lshl_add_u64 v[138:139], v[138:139], 0, v[0:1]
	v_lshlrev_b32_e32 v0, 11, v140
	v_lshl_add_u64 v[140:141], v[138:139], 0, v[0:1]
	s_mov_b64 s[50:51], 0
	s_waitcnt lgkmcnt(0)
	global_store_dwordx4 v[140:141], v[130:133], off
	ds_read_b128 v[130:133], v137 offset:1152
	v_or_b32_e32 v140, 0x4000, v0
	v_mov_b32_e32 v141, v1
	v_lshl_add_u64 v[140:141], v[138:139], 0, v[140:141]
	s_waitcnt lgkmcnt(0)
	global_store_dwordx4 v[140:141], v[130:133], off
	ds_read_b128 v[130:133], v137 offset:2304
	v_or_b32_e32 v140, 0x8000, v0
	v_mov_b32_e32 v141, v1
	v_lshl_add_u64 v[140:141], v[138:139], 0, v[140:141]
	s_waitcnt lgkmcnt(0)
	global_store_dwordx4 v[140:141], v[130:133], off
	ds_read_b128 v[130:133], v137 offset:3456
	v_or_b32_e32 v140, 0xc000, v0
	v_mov_b32_e32 v141, v1
	v_lshl_add_u64 v[140:141], v[138:139], 0, v[140:141]
	s_waitcnt lgkmcnt(0)
	global_store_dwordx4 v[140:141], v[130:133], off
	ds_read_b128 v[130:133], v137 offset:4608
	v_or_b32_e32 v140, 0x10000, v0
	v_mov_b32_e32 v141, v1
	v_lshl_add_u64 v[140:141], v[138:139], 0, v[140:141]
	s_waitcnt lgkmcnt(0)
	global_store_dwordx4 v[140:141], v[130:133], off
	ds_read_b128 v[130:133], v137 offset:5760
	v_or_b32_e32 v140, 0x14000, v0
	v_mov_b32_e32 v141, v1
	v_lshl_add_u64 v[140:141], v[138:139], 0, v[140:141]
	s_waitcnt lgkmcnt(0)
	global_store_dwordx4 v[140:141], v[130:133], off
	ds_read_b128 v[130:133], v137 offset:6912
	v_or_b32_e32 v140, 0x18000, v0
	v_mov_b32_e32 v141, v1
	v_lshl_add_u64 v[140:141], v[138:139], 0, v[140:141]
	s_waitcnt lgkmcnt(0)
	global_store_dwordx4 v[140:141], v[130:133], off
	ds_read_b128 v[130:133], v137 offset:8064
	v_or_b32_e32 v140, 0x1c000, v0
	v_mov_b32_e32 v141, v1
	v_lshl_add_u64 v[140:141], v[138:139], 0, v[140:141]
	s_waitcnt lgkmcnt(0)
	global_store_dwordx4 v[140:141], v[130:133], off
	ds_read_b128 v[130:133], v137 offset:9216
	v_or_b32_e32 v140, 0x20000, v0
	v_mov_b32_e32 v141, v1
	v_lshl_add_u64 v[140:141], v[138:139], 0, v[140:141]
	s_waitcnt lgkmcnt(0)
	global_store_dwordx4 v[140:141], v[130:133], off
	ds_read_b128 v[130:133], v137 offset:10368
	v_or_b32_e32 v140, 0x24000, v0
	v_mov_b32_e32 v141, v1
	v_lshl_add_u64 v[140:141], v[138:139], 0, v[140:141]
	s_waitcnt lgkmcnt(0)
	global_store_dwordx4 v[140:141], v[130:133], off
	ds_read_b128 v[130:133], v137 offset:11520
	v_or_b32_e32 v140, 0x28000, v0
	v_mov_b32_e32 v141, v1
	v_lshl_add_u64 v[140:141], v[138:139], 0, v[140:141]
	s_waitcnt lgkmcnt(0)
	global_store_dwordx4 v[140:141], v[130:133], off
	ds_read_b128 v[130:133], v137 offset:12672
	v_or_b32_e32 v140, 0x2c000, v0
	v_mov_b32_e32 v141, v1
	v_lshl_add_u64 v[140:141], v[138:139], 0, v[140:141]
	s_waitcnt lgkmcnt(0)
	global_store_dwordx4 v[140:141], v[130:133], off
	ds_read_b128 v[130:133], v137 offset:13824
	v_or_b32_e32 v140, 0x30000, v0
	v_mov_b32_e32 v141, v1
	v_lshl_add_u64 v[140:141], v[138:139], 0, v[140:141]
	s_waitcnt lgkmcnt(0)
	global_store_dwordx4 v[140:141], v[130:133], off
	ds_read_b128 v[130:133], v137 offset:14976
	v_or_b32_e32 v140, 0x34000, v0
	v_mov_b32_e32 v141, v1
	v_lshl_add_u64 v[140:141], v[138:139], 0, v[140:141]
	s_waitcnt lgkmcnt(0)
	global_store_dwordx4 v[140:141], v[130:133], off
	ds_read_b128 v[130:133], v137 offset:16128
	v_or_b32_e32 v140, 0x38000, v0
	v_mov_b32_e32 v141, v1
	v_lshl_add_u64 v[140:141], v[138:139], 0, v[140:141]
	v_or_b32_e32 v0, 0x3c000, v0
	s_waitcnt lgkmcnt(0)
	global_store_dwordx4 v[140:141], v[130:133], off
	ds_read_b128 v[130:133], v137 offset:17280
	v_lshl_add_u64 v[138:139], v[138:139], 0, v[0:1]
	s_waitcnt lgkmcnt(0)
	global_store_dwordx4 v[138:139], v[130:133], off
	s_waitcnt lgkmcnt(0)
	s_barrier
